# nt hint on the read-once residual loads of the Wo GEMM epilogue (f32 x in layer 0)
# baseline (speedup 1.0000x reference)
.LBB0_395:
	v_lshl_or_b32 v214, s43, 8, v245
	v_lshl_add_u32 v220, s44, 8, v1
	v_ashrrev_i32_e32 v215, 31, v214
	v_ashrrev_i32_e32 v221, 31, v220
	v_cndmask_b32_e64 v130, 0, 1, s[16:17]
	v_cmp_ne_u32_e64 s[6:7], 1, v130
	s_andn2_b64 vcc, exec, s[16:17]
	v_lshl_add_u64 v[216:217], v[214:215], 2, s[8:9]
	v_or_b32_e32 v226, 16, v220
	v_or_b32_e32 v224, 32, v220
	v_or_b32_e32 v222, 48, v220
	v_lshlrev_b64 v[228:229], 11, v[220:221]
	s_cbranch_vccnz .LBB0_420
	v_lshlrev_b64 v[130:131], 12, v[220:221]
	v_lshl_add_u64 v[130:131], v[216:217], 0, v[130:131]
	v_ashrrev_i32_e32 v227, 31, v226
	global_load_dwordx4 v[186:189], v[130:131], off offset:16 nt
	global_load_dwordx4 v[190:193], v[130:131], off nt
	global_load_dwordx4 v[178:181], v[130:131], off offset:528 nt
	global_load_dwordx4 v[182:185], v[130:131], off offset:512 nt
	v_lshlrev_b64 v[130:131], 12, v[226:227]
	v_lshl_add_u64 v[130:131], v[216:217], 0, v[130:131]
	v_ashrrev_i32_e32 v225, 31, v224
	global_load_dwordx4 v[170:173], v[130:131], off offset:16 nt
	global_load_dwordx4 v[174:177], v[130:131], off nt
	global_load_dwordx4 v[162:165], v[130:131], off offset:528 nt
	global_load_dwordx4 v[166:169], v[130:131], off offset:512 nt
	v_lshlrev_b64 v[130:131], 12, v[224:225]
	v_lshl_add_u64 v[130:131], v[216:217], 0, v[130:131]
	v_ashrrev_i32_e32 v223, 31, v222
	global_load_dwordx4 v[154:157], v[130:131], off offset:16 nt
	global_load_dwordx4 v[158:161], v[130:131], off nt
	global_load_dwordx4 v[146:149], v[130:131], off offset:528 nt
	global_load_dwordx4 v[150:153], v[130:131], off offset:512 nt
	v_lshlrev_b64 v[130:131], 12, v[222:223]
	v_lshl_add_u64 v[134:135], v[216:217], 0, v[130:131]
	global_load_dwordx4 v[138:141], v[134:135], off offset:16 nt
	global_load_dwordx4 v[142:145], v[134:135], off nt
	global_load_dwordx4 v[130:133], v[134:135], off offset:528 nt
	s_nop 0
	global_load_dwordx4 v[134:137], v[134:135], off offset:512 nt
	v_lshlrev_b64 v[230:231], 11, v[220:221]
	v_lshl_add_u64 v[218:219], v[214:215], 1, s[80:81]
	s_cbranch_execnz .LBB0_398
.LBB0_397:
	v_ashrrev_i32_e32 v227, 31, v226
	v_ashrrev_i32_e32 v225, 31, v224
	v_ashrrev_i32_e32 v223, 31, v222
	s_waitcnt vmcnt(0)
	v_lshlrev_b64 v[138:139], 11, v[226:227]
	v_lshl_add_u64 v[134:135], v[218:219], 0, v[228:229]
	v_lshlrev_b64 v[140:141], 11, v[224:225]
	v_lshlrev_b64 v[142:143], 11, v[222:223]
	v_lshl_add_u64 v[144:145], v[218:219], 0, v[138:139]
	global_load_dwordx4 v[130:133], v[134:135], off nt
	v_lshl_add_u64 v[150:151], v[218:219], 0, v[140:141]
	global_load_dwordx4 v[134:137], v[134:135], off offset:256
	v_lshl_add_u64 v[152:153], v[218:219], 0, v[142:143]
	global_load_dwordx4 v[138:141], v[144:145], off nt
	s_nop 0
	global_load_dwordx4 v[142:145], v[144:145], off offset:256
	s_nop 0
	global_load_dwordx4 v[146:149], v[150:151], off nt
	global_load_dwordx4 v[248:251], v[150:151], off offset:256
	global_load_dwordx4 v[194:197], v[152:153], off nt
	global_load_dwordx4 v[198:201], v[152:153], off offset:256
	v_mov_b64_e32 v[230:231], v[228:229]
	s_waitcnt vmcnt(0)
	v_lshlrev_b32_e32 v190, 16, v130
	v_and_b32_e32 v191, 0xffff0000, v130
	v_lshlrev_b32_e32 v192, 16, v131
	v_and_b32_e32 v193, 0xffff0000, v131
	v_lshlrev_b32_e32 v186, 16, v132
	v_and_b32_e32 v187, 0xffff0000, v132
	v_lshlrev_b32_e32 v188, 16, v133
	v_and_b32_e32 v189, 0xffff0000, v133
	v_lshlrev_b32_e32 v182, 16, v134
	v_and_b32_e32 v183, 0xffff0000, v134
	v_lshlrev_b32_e32 v184, 16, v135
	v_and_b32_e32 v185, 0xffff0000, v135
	v_lshlrev_b32_e32 v178, 16, v136
	v_and_b32_e32 v179, 0xffff0000, v136
	v_lshlrev_b32_e32 v180, 16, v137
	v_and_b32_e32 v181, 0xffff0000, v137
	v_lshlrev_b32_e32 v174, 16, v138
	v_and_b32_e32 v175, 0xffff0000, v138
	v_lshlrev_b32_e32 v176, 16, v139
	v_and_b32_e32 v177, 0xffff0000, v139
	v_lshlrev_b32_e32 v170, 16, v140
	v_and_b32_e32 v171, 0xffff0000, v140
	v_lshlrev_b32_e32 v172, 16, v141
	v_and_b32_e32 v173, 0xffff0000, v141
	v_lshlrev_b32_e32 v166, 16, v142
	v_and_b32_e32 v167, 0xffff0000, v142
	v_lshlrev_b32_e32 v168, 16, v143
	v_and_b32_e32 v169, 0xffff0000, v143
	v_lshlrev_b32_e32 v162, 16, v144
	v_and_b32_e32 v163, 0xffff0000, v144
	v_lshlrev_b32_e32 v164, 16, v145
	v_and_b32_e32 v165, 0xffff0000, v145
	v_lshlrev_b32_e32 v158, 16, v146
	v_and_b32_e32 v159, 0xffff0000, v146
	v_lshlrev_b32_e32 v160, 16, v147
	v_and_b32_e32 v161, 0xffff0000, v147
	v_lshlrev_b32_e32 v154, 16, v148
	v_and_b32_e32 v155, 0xffff0000, v148
	v_lshlrev_b32_e32 v156, 16, v149
	v_and_b32_e32 v157, 0xffff0000, v149
	v_lshlrev_b32_e32 v150, 16, v248
	v_and_b32_e32 v151, 0xffff0000, v248
	v_lshlrev_b32_e32 v152, 16, v249
	v_and_b32_e32 v153, 0xffff0000, v249
	v_lshlrev_b32_e32 v146, 16, v250
	v_and_b32_e32 v147, 0xffff0000, v250
	v_lshlrev_b32_e32 v148, 16, v251
	v_and_b32_e32 v149, 0xffff0000, v251
	v_lshlrev_b32_e32 v142, 16, v194
	v_and_b32_e32 v143, 0xffff0000, v194
	v_lshlrev_b32_e32 v144, 16, v195
	v_and_b32_e32 v145, 0xffff0000, v195
	v_lshlrev_b32_e32 v138, 16, v196
	v_and_b32_e32 v139, 0xffff0000, v196
	v_lshlrev_b32_e32 v140, 16, v197
	v_and_b32_e32 v141, 0xffff0000, v197
	v_lshlrev_b32_e32 v134, 16, v198
	v_and_b32_e32 v135, 0xffff0000, v198
	v_lshlrev_b32_e32 v136, 16, v199
	v_and_b32_e32 v137, 0xffff0000, v199
	v_lshlrev_b32_e32 v130, 16, v200
	v_and_b32_e32 v131, 0xffff0000, v200
	v_lshlrev_b32_e32 v132, 16, v201
	v_and_b32_e32 v133, 0xffff0000, v201

.LBB0_406:
	s_or_b64 exec, exec, s[26:27]
	v_add_u32_e32 v136, 0x80, v220
	v_ashrrev_i32_e32 v137, 31, v136
	s_and_b64 vcc, exec, s[6:7]
	v_add_u32_e32 v134, 0x90, v220
	v_add_u32_e32 v132, 0xa0, v220
	v_add_u32_e32 v130, 0xb0, v220
	v_lshlrev_b64 v[138:139], 11, v[136:137]
	s_cbranch_vccnz .LBB0_421
	v_lshlrev_b64 v[66:67], 12, v[136:137]
	v_lshl_add_u64 v[66:67], v[216:217], 0, v[66:67]
	v_ashrrev_i32_e32 v135, 31, v134
	global_load_dwordx4 v[122:125], v[66:67], off offset:16 nt
	global_load_dwordx4 v[126:129], v[66:67], off nt
	global_load_dwordx4 v[114:117], v[66:67], off offset:528 nt
	global_load_dwordx4 v[118:121], v[66:67], off offset:512 nt
	v_lshlrev_b64 v[66:67], 12, v[134:135]
	v_lshl_add_u64 v[66:67], v[216:217], 0, v[66:67]
	v_ashrrev_i32_e32 v133, 31, v132
	global_load_dwordx4 v[106:109], v[66:67], off offset:16 nt
	global_load_dwordx4 v[110:113], v[66:67], off nt
	global_load_dwordx4 v[98:101], v[66:67], off offset:528 nt
	global_load_dwordx4 v[102:105], v[66:67], off offset:512 nt
	v_lshlrev_b64 v[66:67], 12, v[132:133]
	v_lshl_add_u64 v[66:67], v[216:217], 0, v[66:67]
	v_ashrrev_i32_e32 v131, 31, v130
	global_load_dwordx4 v[90:93], v[66:67], off offset:16 nt
	global_load_dwordx4 v[94:97], v[66:67], off nt
	global_load_dwordx4 v[82:85], v[66:67], off offset:528 nt
	global_load_dwordx4 v[86:89], v[66:67], off offset:512 nt
	v_lshlrev_b64 v[66:67], 12, v[130:131]
	v_lshl_add_u64 v[70:71], v[216:217], 0, v[66:67]
	global_load_dwordx4 v[74:77], v[70:71], off offset:16 nt
	global_load_dwordx4 v[78:81], v[70:71], off nt
	global_load_dwordx4 v[66:69], v[70:71], off offset:528 nt
	s_nop 0
	global_load_dwordx4 v[70:73], v[70:71], off offset:512 nt
	v_lshlrev_b64 v[140:141], 11, v[136:137]
	s_cbranch_execnz .LBB0_409
.LBB0_408:
	v_ashrrev_i32_e32 v135, 31, v134
	v_ashrrev_i32_e32 v133, 31, v132
	v_ashrrev_i32_e32 v131, 31, v130
	s_waitcnt vmcnt(3)
	v_lshlrev_b64 v[74:75], 11, v[134:135]
	s_waitcnt vmcnt(0)
	v_lshl_add_u64 v[70:71], v[218:219], 0, v[138:139]
	v_lshlrev_b64 v[76:77], 11, v[132:133]
	v_lshlrev_b64 v[78:79], 11, v[130:131]
	v_lshl_add_u64 v[80:81], v[218:219], 0, v[74:75]
	global_load_dwordx4 v[66:69], v[70:71], off nt
	v_lshl_add_u64 v[86:87], v[218:219], 0, v[76:77]
	global_load_dwordx4 v[70:73], v[70:71], off offset:256
	v_lshl_add_u64 v[88:89], v[218:219], 0, v[78:79]
	global_load_dwordx4 v[74:77], v[80:81], off nt
	s_nop 0
	global_load_dwordx4 v[78:81], v[80:81], off offset:256
	s_nop 0
	global_load_dwordx4 v[82:85], v[86:87], off nt
	global_load_dwordx4 v[140:143], v[86:87], off offset:256
	global_load_dwordx4 v[144:147], v[88:89], off nt
	global_load_dwordx4 v[148:151], v[88:89], off offset:256
	s_waitcnt vmcnt(0)
	v_lshlrev_b32_e32 v126, 16, v66
	v_and_b32_e32 v127, 0xffff0000, v66
	v_lshlrev_b32_e32 v128, 16, v67
	v_and_b32_e32 v129, 0xffff0000, v67
	v_lshlrev_b32_e32 v122, 16, v68
	v_and_b32_e32 v123, 0xffff0000, v68
	v_lshlrev_b32_e32 v124, 16, v69
	v_and_b32_e32 v125, 0xffff0000, v69
	v_lshlrev_b32_e32 v118, 16, v70
	v_and_b32_e32 v119, 0xffff0000, v70
	v_lshlrev_b32_e32 v120, 16, v71
	v_and_b32_e32 v121, 0xffff0000, v71
	v_lshlrev_b32_e32 v114, 16, v72
	v_and_b32_e32 v115, 0xffff0000, v72
	v_lshlrev_b32_e32 v116, 16, v73
	v_and_b32_e32 v117, 0xffff0000, v73
	v_lshlrev_b32_e32 v110, 16, v74
	v_and_b32_e32 v111, 0xffff0000, v74
	v_lshlrev_b32_e32 v112, 16, v75
	v_and_b32_e32 v113, 0xffff0000, v75
	v_lshlrev_b32_e32 v106, 16, v76
	v_and_b32_e32 v107, 0xffff0000, v76
	v_lshlrev_b32_e32 v108, 16, v77
	v_and_b32_e32 v109, 0xffff0000, v77
	v_lshlrev_b32_e32 v102, 16, v78
	v_and_b32_e32 v103, 0xffff0000, v78
	v_lshlrev_b32_e32 v104, 16, v79
	v_and_b32_e32 v105, 0xffff0000, v79
	v_lshlrev_b32_e32 v98, 16, v80
	v_and_b32_e32 v99, 0xffff0000, v80
	v_lshlrev_b32_e32 v100, 16, v81
	v_and_b32_e32 v101, 0xffff0000, v81
	v_lshlrev_b32_e32 v94, 16, v82
	v_and_b32_e32 v95, 0xffff0000, v82
	v_lshlrev_b32_e32 v96, 16, v83
	v_and_b32_e32 v97, 0xffff0000, v83
	v_lshlrev_b32_e32 v90, 16, v84
	v_and_b32_e32 v91, 0xffff0000, v84
	v_lshlrev_b32_e32 v92, 16, v85
	v_and_b32_e32 v93, 0xffff0000, v85
	v_lshlrev_b32_e32 v86, 16, v140
	v_and_b32_e32 v87, 0xffff0000, v140
	v_lshlrev_b32_e32 v88, 16, v141
	v_and_b32_e32 v89, 0xffff0000, v141
	v_lshlrev_b32_e32 v82, 16, v142
	v_and_b32_e32 v83, 0xffff0000, v142
	v_lshlrev_b32_e32 v84, 16, v143
	v_and_b32_e32 v85, 0xffff0000, v143
	v_lshlrev_b32_e32 v78, 16, v144
	v_and_b32_e32 v79, 0xffff0000, v144
	v_lshlrev_b32_e32 v80, 16, v145
	v_and_b32_e32 v81, 0xffff0000, v145
	v_lshlrev_b32_e32 v74, 16, v146
	v_and_b32_e32 v75, 0xffff0000, v146
	v_lshlrev_b32_e32 v76, 16, v147
	v_and_b32_e32 v77, 0xffff0000, v147
	v_lshlrev_b32_e32 v70, 16, v148
	v_and_b32_e32 v71, 0xffff0000, v148
	v_lshlrev_b32_e32 v72, 16, v149
	v_and_b32_e32 v73, 0xffff0000, v149
	v_lshlrev_b32_e32 v66, 16, v150
	v_and_b32_e32 v67, 0xffff0000, v150
	v_lshlrev_b32_e32 v68, 16, v151
	v_and_b32_e32 v69, 0xffff0000, v151
	v_mov_b64_e32 v[140:141], v[138:139]
